# P7 K-loop load segments: saddr-form LDS-DMA (SGPR base + 32-bit lane offset) instead of a 64-bit VALU add per DMA; base+0x80 variants via SALU in spare SGPR pairs
# baseline (speedup 1.0000x reference)
; #define PG8_STAGE(bufoff, gbase, voff) do { _Pragma("unroll") for (int _i = 0; _i < 2; ++_i) \
;         __builtin_amdgcn_global_load_lds((const unsigned*)((const char*)(gbase) + (voff)[_i]), (PG8_LAS unsigned*)(lds + (bufoff) + ldsw + _i * 8192), 16, 0, 0); } while (0)
; #define PG8_LDA(dst, b, h) do { _Pragma("unroll") for (int m = 0; m < 4; ++m) _Pragma("unroll") for (int k = 0; k < 2; ++k) dst[m][k] = *(const PG8_LAS bf16x8*)(lds + PG8_SA(b, h) + aoff + m * 2048 + k * 1024); } while (0)
; #define PG8_LDB(dst, b, h) do { _Pragma("unroll") for (int n = 0; n < 2; ++n) _Pragma("unroll") for (int k = 0; k < 2; ++k) dst[n][k] = *(const PG8_LAS bf16x8*)(lds + PG8_SB(b, h) + boff + n * 2048 + k * 1024); } while (0)
; #define PG8_MMA(ai, bj, At, Bt) do { __builtin_amdgcn_s_setprio(1); _Pragma("unroll") for (int m = 0; m < 4; ++m) _Pragma("unroll") for (int n = 0; n < 2; ++n) _Pragma("unroll") for (int k = 0; k < 2; ++k) \
;         acc[ai][bj][m][n] = __builtin_amdgcn_mfma_f32_16x16x32_bf16(Bt[n][k], At[m][k], acc[ai][bj][m][n], 0, 0, 0); __builtin_amdgcn_s_setprio(0); } while (0)
; template <class Epi, class Sched, bool ALIGN_EPI = false, bool SP2 = false>
; __device__ __forceinline__ void gemm_phase(PG8_LAS unsigned char* lds, const Gemm g, const Sched& S, const Epi& E, int wave_in) {
;     ...
;         const char* nA = has_next ? (const char*)g.A + (size_t)(nxt.pm >> g.ash) * g.astride + (size_t)nxt.pm * tstep : cA; const char* nB = has_next ? (const char*)g.Bt + (size_t)(nxt.pm >> g.bsh) * g.bstride + (size_t)nxt.pn * tstep : cB;
;         for (int t = 0; t < nt; t += 2) {
;             const bool last = (t == nt - 2);
;             const char* a1 = cA + (size_t)(t + 1) * kstep;
;             const char* a2 = last ? nA : cA + (size_t)(t + 2) * kstep; const char* b2 = last ? nB : cB + (size_t)(t + 2) * kstep;
;             const char* a3 = a2 + kstep; const char* b3 = b2 + kstep;
;             if (last && has_next) S.a_ready(nxt);
;             if constexpr (SP2) {
;             PG8_LDB(B0, 0, 0); PG8_LDB(B1, 0, 1); PG8_SCHED; PG8_LDA(At, 0, 0); PG8_STAGE(PG8_SA(1, 1), a1 + hstep, voffA);
;             PG8_WAIT_V(8); PG8_WAIT_L(0); PG8_BAR; PG8_MMA(0, 0, At, B0); PG8_MMA(0, 1, At, B1); PG8_BAR; PG8_SCHED;
;             PG8_LDA(At, 0, 1); PG8_STAGE(PG8_SB(0, 0), b2, voffB); PG8_STAGE(PG8_SB(0, 1), b2 + hstep, voffB); PG8_STAGE(PG8_SA(0, 0), a2, voffA);
.LBB0_896:
	s_ashr_i32 s11, s10, 31
	s_lshl_b64 s[18:19], s[10:11], 19
	s_add_u32 s66, s6, s18
	s_addc_u32 s67, s72, s19
	s_and_b64 s[18:19], s[46:47], exec
	s_cselect_b32 s11, s67, s1
	s_cselect_b32 s34, s66, s0
	s_ashr_i32 s5, s4, 31
	s_lshl_b64 s[18:19], s[4:5], 19
	s_add_u32 s38, s73, s18
	s_addc_u32 s39, s74, s19
	s_and_b64 s[18:19], s[46:47], exec
	s_cselect_b32 s5, s39, s79
	s_cselect_b32 s53, s38, s78
	s_add_u32 s81, s78, 0x100
	s_addc_u32 s18, s79, 0
	s_add_u32 vcc_lo, s0, 0x40080
	s_addc_u32 vcc_hi, s1, 0
	s_mov_b32 s19, -2
	s_add_u32 s0, vcc_lo, 0xfffc0080
	s_addc_u32 s1, vcc_hi, -1
	s_add_i32 s76, s35, 0x100
	s_cmp_eq_u32 s19, 12
	s_cselect_b32 s79, s11, s1
	s_cselect_b32 s78, s34, s0
	s_cselect_b32 s1, s5, s18
	s_cselect_b32 s0, s53, s81
	s_add_i32 s29, s90, 0x100
	v_add_u32_e32 v140, s76, v207
	v_add_u32_e32 v156, s29, v207
	ds_read_b128 v[128:131], v140
	ds_read_b128 v[132:135], v140 offset:1024
	ds_read_b128 v[136:139], v140 offset:2048
	ds_read_b128 v[140:143], v140 offset:3072
	ds_read_b128 v[144:147], v156
	ds_read_b128 v[148:151], v156 offset:1024
	ds_read_b128 v[152:155], v156 offset:2048
	ds_read_b128 v[156:159], v156 offset:3072
	s_add_i32 m0, s33, 0xc000
	ds_read_b128 v[160:163], v219
	ds_read_b128 v[164:167], v219 offset:1024
	ds_read_b128 v[178:181], v219 offset:2048
	ds_read_b128 v[182:185], v219 offset:3072
	ds_read_b128 v[186:189], v219 offset:4096
	ds_read_b128 v[198:201], v219 offset:5120
	ds_read_b128 v[202:205], v219 offset:6144
	ds_read_b128 v[220:223], v219 offset:7168
	global_load_lds_dwordx4 v176, vcc
	s_add_i32 m0, s33, 0xe000
	s_nop 0
	global_load_lds_dwordx4 v174, vcc
	s_waitcnt vmcnt(8)
	s_waitcnt lgkmcnt(0)
	s_barrier
	s_setprio 1
	s_waitcnt lgkmcnt(0)
	v_mfma_f32_16x16x32_bf16 v[124:127], v[128:131], v[160:163], 0
	v_mfma_f32_16x16x32_bf16 v[60:63], v[136:139], v[160:163], 0
	v_mfma_f32_16x16x32_bf16 v[116:119], v[128:131], v[178:181], 0
	v_mfma_f32_16x16x32_bf16 v[52:55], v[136:139], v[178:181], 0
	v_mfma_f32_16x16x32_bf16 v[108:111], v[128:131], v[186:189], 0
	v_mfma_f32_16x16x32_bf16 v[44:47], v[136:139], v[186:189], 0
	v_mfma_f32_16x16x32_bf16 v[100:103], v[128:131], v[202:205], 0
	v_mfma_f32_16x16x32_bf16 v[36:39], v[136:139], v[202:205], 0
	v_mfma_f32_16x16x32_bf16 v[124:127], v[132:135], v[164:167], v[124:127]
	v_mfma_f32_16x16x32_bf16 v[60:63], v[140:143], v[164:167], v[60:63]
	v_mfma_f32_16x16x32_bf16 v[116:119], v[132:135], v[182:185], v[116:119]
	v_mfma_f32_16x16x32_bf16 v[52:55], v[140:143], v[182:185], v[52:55]
	v_mfma_f32_16x16x32_bf16 v[108:111], v[132:135], v[198:201], v[108:111]
	v_mfma_f32_16x16x32_bf16 v[44:47], v[140:143], v[198:201], v[44:47]
	v_mfma_f32_16x16x32_bf16 v[100:103], v[132:135], v[220:223], v[100:103]
	v_mfma_f32_16x16x32_bf16 v[36:39], v[140:143], v[220:223], v[36:39]
	s_setprio 0
	s_setprio 1
	v_mfma_f32_16x16x32_bf16 v[120:123], v[144:147], v[160:163], 0
	v_mfma_f32_16x16x32_bf16 v[56:59], v[152:155], v[160:163], 0
	v_mfma_f32_16x16x32_bf16 v[112:115], v[144:147], v[178:181], 0
	v_mfma_f32_16x16x32_bf16 v[48:51], v[152:155], v[178:181], 0
	v_mfma_f32_16x16x32_bf16 v[104:107], v[144:147], v[186:189], 0
	v_mfma_f32_16x16x32_bf16 v[40:43], v[152:155], v[186:189], 0
	v_mfma_f32_16x16x32_bf16 v[96:99], v[144:147], v[202:205], 0
	v_mfma_f32_16x16x32_bf16 v[32:35], v[152:155], v[202:205], 0
	v_mfma_f32_16x16x32_bf16 v[120:123], v[148:151], v[164:167], v[120:123]
	v_mfma_f32_16x16x32_bf16 v[56:59], v[156:159], v[164:167], v[56:59]
	v_mfma_f32_16x16x32_bf16 v[112:115], v[148:151], v[182:185], v[112:115]
	v_mfma_f32_16x16x32_bf16 v[48:51], v[156:159], v[182:185], v[48:51]
	v_mfma_f32_16x16x32_bf16 v[104:107], v[148:151], v[198:201], v[104:107]
	v_mfma_f32_16x16x32_bf16 v[40:43], v[156:159], v[198:201], v[40:43]
	v_mfma_f32_16x16x32_bf16 v[96:99], v[148:151], v[220:223], v[96:99]
	v_mfma_f32_16x16x32_bf16 v[32:35], v[156:159], v[220:223], v[32:35]
	s_setprio 0
	s_barrier
	s_add_i32 s76, s76, s75
	s_mov_b32 m0, s76
	ds_read_b128 v[160:163], v219 offset:16384
	ds_read_b128 v[164:167], v219 offset:17408
	ds_read_b128 v[178:181], v219 offset:18432
	ds_read_b128 v[182:185], v219 offset:19456
	ds_read_b128 v[186:189], v219 offset:20480
	ds_read_b128 v[198:201], v219 offset:21504
	ds_read_b128 v[202:205], v219 offset:22528
	ds_read_b128 v[220:223], v219 offset:23552
	global_load_lds_dwordx4 v192, s[0:1]
	s_add_i32 m0, s76, 0x2000
	s_add_u32 s76, s0, 0x40000
	s_addc_u32 s77, s1, 0
	s_add_i32 s29, s29, s75
	global_load_lds_dwordx4 v168, s[0:1]
	s_mov_b32 m0, s29
	s_nop 0
	global_load_lds_dwordx4 v192, s[76:77]
	s_add_i32 m0, s29, 0x2000
	s_nop 0
	global_load_lds_dwordx4 v168, s[76:77]
	s_mov_b32 m0, s33
	s_nop 0
	global_load_lds_dwordx4 v172, s[78:79]
	s_mov_b32 m0, s62
	s_nop 0
	global_load_lds_dwordx4 v170, s[78:79]
	s_waitcnt vmcnt(8)
	s_waitcnt lgkmcnt(0)
	s_barrier
; #define PG8_STAGE(bufoff, gbase, voff) do { _Pragma("unroll") for (int _i = 0; _i < 2; ++_i) \
;         __builtin_amdgcn_global_load_lds((const unsigned*)((const char*)(gbase) + (voff)[_i]), (PG8_LAS unsigned*)(lds + (bufoff) + ldsw + _i * 8192), 16, 0, 0); } while (0)
; #define PG8_LDA(dst, b, h) do { _Pragma("unroll") for (int m = 0; m < 4; ++m) _Pragma("unroll") for (int k = 0; k < 2; ++k) dst[m][k] = *(const PG8_LAS bf16x8*)(lds + PG8_SA(b, h) + aoff + m * 2048 + k * 1024); } while (0)
; #define PG8_LDB(dst, b, h) do { _Pragma("unroll") for (int n = 0; n < 2; ++n) _Pragma("unroll") for (int k = 0; k < 2; ++k) dst[n][k] = *(const PG8_LAS bf16x8*)(lds + PG8_SB(b, h) + boff + n * 2048 + k * 1024); } while (0)
; #define PG8_MMA(ai, bj, At, Bt) do { __builtin_amdgcn_s_setprio(1); _Pragma("unroll") for (int m = 0; m < 4; ++m) _Pragma("unroll") for (int n = 0; n < 2; ++n) _Pragma("unroll") for (int k = 0; k < 2; ++k) \
;         acc[ai][bj][m][n] = __builtin_amdgcn_mfma_f32_16x16x32_bf16(Bt[n][k], At[m][k], acc[ai][bj][m][n], 0, 0, 0); __builtin_amdgcn_s_setprio(0); } while (0)
; #define PG8_WAIT_V(n) asm volatile("s_waitcnt vmcnt(" #n ")" ::: "memory")
; #define PG8_WAIT_L(n) asm volatile("s_waitcnt lgkmcnt(" #n ")" ::: "memory")
; #define PG8_BAR __builtin_amdgcn_s_barrier()
; #define PG8_SCHED __builtin_amdgcn_sched_barrier(0)
; template <class Epi, class Sched, bool ALIGN_EPI = false, bool SP2 = false>
; __device__ __forceinline__ void gemm_phase(PG8_LAS unsigned char* lds, const Gemm g, const Sched& S, const Epi& E, int wave_in) {
;     ...
;             PG8_WAIT_V(8); PG8_WAIT_L(0); PG8_BAR; PG8_MMA(1, 0, At, B0); PG8_MMA(1, 1, At, B1); PG8_BAR; PG8_SCHED;
;             PG8_LDB(B0, 1, 0); PG8_LDB(B1, 1, 1); PG8_SCHED; PG8_LDA(At, 1, 0); PG8_STAGE(PG8_SA(0, 1), a2 + hstep, voffA);
;             PG8_WAIT_V(8); PG8_WAIT_L(0); PG8_BAR; PG8_MMA(0, 0, At, B0); PG8_MMA(0, 1, At, B1); PG8_BAR; PG8_SCHED;
	s_setprio 1
	s_waitcnt lgkmcnt(0)
	v_mfma_f32_16x16x32_bf16 v[92:95], v[128:131], v[160:163], 0
	v_mfma_f32_16x16x32_bf16 v[28:31], v[136:139], v[160:163], 0
	v_mfma_f32_16x16x32_bf16 v[84:87], v[128:131], v[178:181], 0
	v_mfma_f32_16x16x32_bf16 v[20:23], v[136:139], v[178:181], 0
	v_mfma_f32_16x16x32_bf16 v[76:79], v[128:131], v[186:189], 0
	v_mfma_f32_16x16x32_bf16 v[12:15], v[136:139], v[186:189], 0
	v_mfma_f32_16x16x32_bf16 v[68:71], v[128:131], v[202:205], 0
	v_mfma_f32_16x16x32_bf16 v[4:7], v[136:139], v[202:205], 0
	v_mfma_f32_16x16x32_bf16 v[92:95], v[132:135], v[164:167], v[92:95]
	v_mfma_f32_16x16x32_bf16 v[28:31], v[140:143], v[164:167], v[28:31]
	v_mfma_f32_16x16x32_bf16 v[84:87], v[132:135], v[182:185], v[84:87]
	v_mfma_f32_16x16x32_bf16 v[20:23], v[140:143], v[182:185], v[20:23]
	v_mfma_f32_16x16x32_bf16 v[76:79], v[132:135], v[198:201], v[76:79]
	v_mfma_f32_16x16x32_bf16 v[12:15], v[140:143], v[198:201], v[12:15]
	v_mfma_f32_16x16x32_bf16 v[68:71], v[132:135], v[220:223], v[68:71]
	v_mfma_f32_16x16x32_bf16 v[4:7], v[140:143], v[220:223], v[4:7]
	s_setprio 0
	s_setprio 1
	v_mfma_f32_16x16x32_bf16 v[88:91], v[144:147], v[160:163], 0
	v_mfma_f32_16x16x32_bf16 v[24:27], v[152:155], v[160:163], 0
	v_mfma_f32_16x16x32_bf16 v[80:83], v[144:147], v[178:181], 0
	v_mfma_f32_16x16x32_bf16 v[16:19], v[152:155], v[178:181], 0
	v_mfma_f32_16x16x32_bf16 v[72:75], v[144:147], v[186:189], 0
	v_mfma_f32_16x16x32_bf16 v[8:11], v[152:155], v[186:189], 0
	v_mfma_f32_16x16x32_bf16 v[64:67], v[144:147], v[202:205], 0
	v_mfma_f32_16x16x32_bf16 v[0:3], v[152:155], v[202:205], 0
	v_mfma_f32_16x16x32_bf16 v[88:91], v[148:151], v[164:167], v[88:91]
	v_mfma_f32_16x16x32_bf16 v[24:27], v[156:159], v[164:167], v[24:27]
	v_mfma_f32_16x16x32_bf16 v[80:83], v[148:151], v[182:185], v[80:83]
	v_mfma_f32_16x16x32_bf16 v[16:19], v[156:159], v[182:185], v[16:19]
	v_mfma_f32_16x16x32_bf16 v[72:75], v[148:151], v[198:201], v[72:75]
	v_mfma_f32_16x16x32_bf16 v[8:11], v[156:159], v[198:201], v[8:11]
	v_mfma_f32_16x16x32_bf16 v[64:67], v[148:151], v[220:223], v[64:67]
	v_mfma_f32_16x16x32_bf16 v[0:3], v[156:159], v[220:223], v[0:3]
	s_setprio 0
	s_barrier
	s_add_i32 s29, s65, 0x100
	s_add_i32 s2, s52, 0x100
	v_add_u32_e32 v140, s29, v207
	v_add_u32_e32 v156, s2, v207
	ds_read_b128 v[128:131], v140
	ds_read_b128 v[132:135], v140 offset:1024
	ds_read_b128 v[136:139], v140 offset:2048
	ds_read_b128 v[140:143], v140 offset:3072
	ds_read_b128 v[144:147], v156
	ds_read_b128 v[148:151], v156 offset:1024
	ds_read_b128 v[152:155], v156 offset:2048
	ds_read_b128 v[156:159], v156 offset:3072
	s_add_u32 s76, s78, 0x40000
	s_addc_u32 s77, s79, 0
	s_mov_b32 m0, s63
	ds_read_b128 v[160:163], v219 offset:32768
	ds_read_b128 v[164:167], v219 offset:33792
	ds_read_b128 v[178:181], v219 offset:34816
	ds_read_b128 v[182:185], v219 offset:35840
	ds_read_b128 v[186:189], v219 offset:36864
	ds_read_b128 v[198:201], v219 offset:37888
	ds_read_b128 v[202:205], v219 offset:38912
	ds_read_b128 v[220:223], v219 offset:39936
	global_load_lds_dwordx4 v172, s[76:77]
	s_mov_b32 m0, s31
	s_nop 0
	global_load_lds_dwordx4 v170, s[76:77]
	s_waitcnt vmcnt(8)
	s_waitcnt lgkmcnt(0)
	s_barrier
	s_setprio 1
	s_waitcnt lgkmcnt(0)
	v_mfma_f32_16x16x32_bf16 v[124:127], v[128:131], v[160:163], v[124:127]
	v_mfma_f32_16x16x32_bf16 v[60:63], v[136:139], v[160:163], v[60:63]
	v_mfma_f32_16x16x32_bf16 v[116:119], v[128:131], v[178:181], v[116:119]
	v_mfma_f32_16x16x32_bf16 v[52:55], v[136:139], v[178:181], v[52:55]
	v_mfma_f32_16x16x32_bf16 v[108:111], v[128:131], v[186:189], v[108:111]
	v_mfma_f32_16x16x32_bf16 v[44:47], v[136:139], v[186:189], v[44:47]
	v_mfma_f32_16x16x32_bf16 v[100:103], v[128:131], v[202:205], v[100:103]
	v_mfma_f32_16x16x32_bf16 v[36:39], v[136:139], v[202:205], v[36:39]
	v_mfma_f32_16x16x32_bf16 v[124:127], v[132:135], v[164:167], v[124:127]
	v_mfma_f32_16x16x32_bf16 v[60:63], v[140:143], v[164:167], v[60:63]
	v_mfma_f32_16x16x32_bf16 v[116:119], v[132:135], v[182:185], v[116:119]
	v_mfma_f32_16x16x32_bf16 v[52:55], v[140:143], v[182:185], v[52:55]
	v_mfma_f32_16x16x32_bf16 v[108:111], v[132:135], v[198:201], v[108:111]
	v_mfma_f32_16x16x32_bf16 v[44:47], v[140:143], v[198:201], v[44:47]
	v_mfma_f32_16x16x32_bf16 v[100:103], v[132:135], v[220:223], v[100:103]
	v_mfma_f32_16x16x32_bf16 v[36:39], v[140:143], v[220:223], v[36:39]
	s_setprio 0
	s_setprio 1
	v_mfma_f32_16x16x32_bf16 v[120:123], v[144:147], v[160:163], v[120:123]
	v_mfma_f32_16x16x32_bf16 v[56:59], v[152:155], v[160:163], v[56:59]
	v_mfma_f32_16x16x32_bf16 v[112:115], v[144:147], v[178:181], v[112:115]
	v_mfma_f32_16x16x32_bf16 v[48:51], v[152:155], v[178:181], v[48:51]
	v_mfma_f32_16x16x32_bf16 v[104:107], v[144:147], v[186:189], v[104:107]
	v_mfma_f32_16x16x32_bf16 v[40:43], v[152:155], v[186:189], v[40:43]
	v_mfma_f32_16x16x32_bf16 v[96:99], v[144:147], v[202:205], v[96:99]
	v_mfma_f32_16x16x32_bf16 v[32:35], v[152:155], v[202:205], v[32:35]
	v_mfma_f32_16x16x32_bf16 v[120:123], v[148:151], v[164:167], v[120:123]
	v_mfma_f32_16x16x32_bf16 v[56:59], v[156:159], v[164:167], v[56:59]
	v_mfma_f32_16x16x32_bf16 v[112:115], v[148:151], v[182:185], v[112:115]
	v_mfma_f32_16x16x32_bf16 v[48:51], v[156:159], v[182:185], v[48:51]
	v_mfma_f32_16x16x32_bf16 v[104:107], v[148:151], v[198:201], v[104:107]
	v_mfma_f32_16x16x32_bf16 v[40:43], v[156:159], v[198:201], v[40:43]
	v_mfma_f32_16x16x32_bf16 v[96:99], v[148:151], v[220:223], v[96:99]
	v_mfma_f32_16x16x32_bf16 v[32:35], v[156:159], v[220:223], v[32:35]
	s_setprio 0
	s_barrier
; #define PG8_STAGE(bufoff, gbase, voff) do { _Pragma("unroll") for (int _i = 0; _i < 2; ++_i) \
;         __builtin_amdgcn_global_load_lds((const unsigned*)((const char*)(gbase) + (voff)[_i]), (PG8_LAS unsigned*)(lds + (bufoff) + ldsw + _i * 8192), 16, 0, 0); } while (0)
; #define PG8_LDA(dst, b, h) do { _Pragma("unroll") for (int m = 0; m < 4; ++m) _Pragma("unroll") for (int k = 0; k < 2; ++k) dst[m][k] = *(const PG8_LAS bf16x8*)(lds + PG8_SA(b, h) + aoff + m * 2048 + k * 1024); } while (0)
; #define PG8_WAIT_V(n) asm volatile("s_waitcnt vmcnt(" #n ")" ::: "memory")
; #define PG8_WAIT_L(n) asm volatile("s_waitcnt lgkmcnt(" #n ")" ::: "memory")
; #define PG8_BAR __builtin_amdgcn_s_barrier()
; template <class Epi, class Sched, bool ALIGN_EPI = false, bool SP2 = false>
; __device__ __forceinline__ void gemm_phase(PG8_LAS unsigned char* lds, const Gemm g, const Sched& S, const Epi& E, int wave_in) {
;     ...
;         for (int t = 0; t < nt; t += 2) {
;             const bool last = (t == nt - 2);
;             const char* a1 = cA + (size_t)(t + 1) * kstep;
;             const char* a2 = last ? nA : cA + (size_t)(t + 2) * kstep; const char* b2 = last ? nB : cB + (size_t)(t + 2) * kstep;
;             const char* a3 = a2 + kstep; const char* b3 = b2 + kstep;
;             if (last && has_next) S.a_ready(nxt);
;             if constexpr (SP2) {
;             PG8_LDB(B0, 0, 0); PG8_LDB(B1, 0, 1); PG8_SCHED; PG8_LDA(At, 0, 0); PG8_STAGE(PG8_SA(1, 1), a1 + hstep, voffA);
;             PG8_WAIT_V(8); PG8_WAIT_L(0); PG8_BAR; PG8_MMA(0, 0, At, B0); PG8_MMA(0, 1, At, B1); PG8_BAR; PG8_SCHED;
;             PG8_LDA(At, 0, 1); PG8_STAGE(PG8_SB(0, 0), b2, voffB); PG8_STAGE(PG8_SB(0, 1), b2 + hstep, voffB); PG8_STAGE(PG8_SA(0, 0), a2, voffA);
;             PG8_WAIT_V(8); PG8_WAIT_L(0); PG8_BAR; PG8_MMA(1, 0, At, B0); PG8_MMA(1, 1, At, B1); PG8_BAR; PG8_SCHED;
;             PG8_LDB(B0, 1, 0); PG8_LDB(B1, 1, 1); PG8_SCHED; PG8_LDA(At, 1, 0); PG8_STAGE(PG8_SA(0, 1), a2 + hstep, voffA);
;             PG8_WAIT_V(8); PG8_WAIT_L(0); PG8_BAR; PG8_MMA(0, 0, At, B0); PG8_MMA(0, 1, At, B1); PG8_BAR; PG8_SCHED;
;             PG8_LDA(At, 1, 1); PG8_STAGE(PG8_SB(1, 0), b3, voffB); PG8_STAGE(PG8_SB(1, 1), b3 + hstep, voffB); PG8_STAGE(PG8_SA(1, 0), a3, voffA);
;             PG8_WAIT_V(8); PG8_WAIT_L(0); PG8_BAR; PG8_MMA(1, 0, At, B0); PG8_MMA(1, 1, At, B1); PG8_BAR; PG8_SCHED;
	s_add_u32 s44, s78, 0x80
	s_addc_u32 s45, s79, 0
	s_add_u32 s42, s0, 0x80
	s_addc_u32 s43, s1, 0
	s_add_i32 s29, s29, s75
	s_mov_b32 m0, s29
	ds_read_b128 v[160:163], v219 offset:49152
	ds_read_b128 v[164:167], v219 offset:50176
	ds_read_b128 v[178:181], v219 offset:51200
	ds_read_b128 v[182:185], v219 offset:52224
	ds_read_b128 v[186:189], v219 offset:53248
	ds_read_b128 v[198:201], v219 offset:54272
	ds_read_b128 v[202:205], v219 offset:55296
	ds_read_b128 v[220:223], v219 offset:56320
	global_load_lds_dwordx4 v192, s[42:43]
	s_add_i32 m0, s29, 0x2000
	s_add_u32 s0, s0, 0x40080
	s_addc_u32 s1, s1, 0
	s_add_i32 s2, s2, s75
	global_load_lds_dwordx4 v168, s[42:43]
	s_mov_b32 m0, s2
	s_nop 0
	global_load_lds_dwordx4 v192, s[0:1]
	s_add_i32 m0, s2, 0x2000
	s_nop 0
	global_load_lds_dwordx4 v168, s[0:1]
	s_mov_b32 m0, s9
	s_nop 0
	global_load_lds_dwordx4 v172, s[44:45]
	s_mov_b32 m0, s96
	s_nop 0
	global_load_lds_dwordx4 v170, s[44:45]
	s_waitcnt vmcnt(8)
	s_waitcnt lgkmcnt(0)
	s_barrier
	s_setprio 1
	s_waitcnt lgkmcnt(0)
	v_mfma_f32_16x16x32_bf16 v[92:95], v[128:131], v[160:163], v[92:95]
	v_mfma_f32_16x16x32_bf16 v[28:31], v[136:139], v[160:163], v[28:31]
	v_mfma_f32_16x16x32_bf16 v[84:87], v[128:131], v[178:181], v[84:87]
	v_mfma_f32_16x16x32_bf16 v[20:23], v[136:139], v[178:181], v[20:23]
	v_mfma_f32_16x16x32_bf16 v[76:79], v[128:131], v[186:189], v[76:79]
	v_mfma_f32_16x16x32_bf16 v[12:15], v[136:139], v[186:189], v[12:15]
	v_mfma_f32_16x16x32_bf16 v[68:71], v[128:131], v[202:205], v[68:71]
	v_mfma_f32_16x16x32_bf16 v[4:7], v[136:139], v[202:205], v[4:7]
	v_mfma_f32_16x16x32_bf16 v[92:95], v[132:135], v[164:167], v[92:95]
	v_mfma_f32_16x16x32_bf16 v[28:31], v[140:143], v[164:167], v[28:31]
	v_mfma_f32_16x16x32_bf16 v[84:87], v[132:135], v[182:185], v[84:87]
	v_mfma_f32_16x16x32_bf16 v[20:23], v[140:143], v[182:185], v[20:23]
	v_mfma_f32_16x16x32_bf16 v[76:79], v[132:135], v[198:201], v[76:79]
	v_mfma_f32_16x16x32_bf16 v[12:15], v[140:143], v[198:201], v[12:15]
	v_mfma_f32_16x16x32_bf16 v[68:71], v[132:135], v[220:223], v[68:71]
	v_mfma_f32_16x16x32_bf16 v[4:7], v[140:143], v[220:223], v[4:7]
	s_setprio 0
	s_setprio 1
	v_mfma_f32_16x16x32_bf16 v[88:91], v[144:147], v[160:163], v[88:91]
	v_mfma_f32_16x16x32_bf16 v[24:27], v[152:155], v[160:163], v[24:27]
	v_mfma_f32_16x16x32_bf16 v[80:83], v[144:147], v[178:181], v[80:83]
	v_mfma_f32_16x16x32_bf16 v[16:19], v[152:155], v[178:181], v[16:19]
	v_mfma_f32_16x16x32_bf16 v[72:75], v[144:147], v[186:189], v[72:75]
	v_mfma_f32_16x16x32_bf16 v[8:11], v[152:155], v[186:189], v[8:11]
	v_mfma_f32_16x16x32_bf16 v[64:67], v[144:147], v[202:205], v[64:67]
	v_mfma_f32_16x16x32_bf16 v[0:3], v[152:155], v[202:205], v[0:3]
	v_mfma_f32_16x16x32_bf16 v[88:91], v[148:151], v[164:167], v[88:91]
	v_mfma_f32_16x16x32_bf16 v[24:27], v[156:159], v[164:167], v[24:27]
	v_mfma_f32_16x16x32_bf16 v[80:83], v[148:151], v[182:185], v[80:83]
	v_mfma_f32_16x16x32_bf16 v[16:19], v[156:159], v[182:185], v[16:19]
	v_mfma_f32_16x16x32_bf16 v[72:75], v[148:151], v[198:201], v[72:75]
	v_mfma_f32_16x16x32_bf16 v[8:11], v[156:159], v[198:201], v[8:11]
	v_mfma_f32_16x16x32_bf16 v[64:67], v[148:151], v[220:223], v[64:67]
	v_mfma_f32_16x16x32_bf16 v[0:3], v[156:159], v[220:223], v[0:3]
	s_setprio 0
	s_barrier
	s_add_i32 s19, s19, 2
	s_add_u32 s81, s81, 0x100
	s_addc_u32 s18, s18, 0
	s_add_u32 vcc_lo, vcc_lo, 0x100
	s_addc_u32 vcc_hi, vcc_hi, 0
	s_cmp_gt_u32 s19, 13
	s_cbranch_scc1 .Lkexit_6
.LBB0_897:
	s_add_u32 s0, vcc_lo, 0xfffc0080
	s_addc_u32 s1, vcc_hi, -1
	s_add_i32 s76, s35, 0x100
	s_cmp_eq_u32 s19, 12
	s_cselect_b32 s79, s11, s1
	s_cselect_b32 s78, s34, s0
	s_cselect_b32 s1, s5, s18
	s_cselect_b32 s0, s53, s81
	s_add_i32 s29, s90, 0x100
	v_add_u32_e32 v140, s76, v207
	v_add_u32_e32 v156, s29, v207
	ds_read_b128 v[128:131], v140
	ds_read_b128 v[132:135], v140 offset:1024
	ds_read_b128 v[136:139], v140 offset:2048
	ds_read_b128 v[140:143], v140 offset:3072
	ds_read_b128 v[144:147], v156
	ds_read_b128 v[148:151], v156 offset:1024
	ds_read_b128 v[152:155], v156 offset:2048
	ds_read_b128 v[156:159], v156 offset:3072
	s_add_i32 m0, s33, 0xc000
	ds_read_b128 v[160:163], v219
	ds_read_b128 v[164:167], v219 offset:1024
	ds_read_b128 v[178:181], v219 offset:2048
	ds_read_b128 v[182:185], v219 offset:3072
	ds_read_b128 v[186:189], v219 offset:4096
	ds_read_b128 v[198:201], v219 offset:5120
	ds_read_b128 v[202:205], v219 offset:6144
	ds_read_b128 v[220:223], v219 offset:7168
	global_load_lds_dwordx4 v176, vcc
	s_add_i32 m0, s33, 0xe000
	s_nop 0
	global_load_lds_dwordx4 v174, vcc
	s_waitcnt vmcnt(8)
	s_waitcnt lgkmcnt(0)
	s_barrier
; #define PG8_STAGE(bufoff, gbase, voff) do { _Pragma("unroll") for (int _i = 0; _i < 2; ++_i) \
;         __builtin_amdgcn_global_load_lds((const unsigned*)((const char*)(gbase) + (voff)[_i]), (PG8_LAS unsigned*)(lds + (bufoff) + ldsw + _i * 8192), 16, 0, 0); } while (0)
; #define PG8_LDA(dst, b, h) do { _Pragma("unroll") for (int m = 0; m < 4; ++m) _Pragma("unroll") for (int k = 0; k < 2; ++k) dst[m][k] = *(const PG8_LAS bf16x8*)(lds + PG8_SA(b, h) + aoff + m * 2048 + k * 1024); } while (0)
; #define PG8_LDB(dst, b, h) do { _Pragma("unroll") for (int n = 0; n < 2; ++n) _Pragma("unroll") for (int k = 0; k < 2; ++k) dst[n][k] = *(const PG8_LAS bf16x8*)(lds + PG8_SB(b, h) + boff + n * 2048 + k * 1024); } while (0)
; #define PG8_MMA(ai, bj, At, Bt) do { __builtin_amdgcn_s_setprio(1); _Pragma("unroll") for (int m = 0; m < 4; ++m) _Pragma("unroll") for (int n = 0; n < 2; ++n) _Pragma("unroll") for (int k = 0; k < 2; ++k) \
;         acc[ai][bj][m][n] = __builtin_amdgcn_mfma_f32_16x16x32_bf16(Bt[n][k], At[m][k], acc[ai][bj][m][n], 0, 0, 0); __builtin_amdgcn_s_setprio(0); } while (0)
; #define PG8_WAIT_V(n) asm volatile("s_waitcnt vmcnt(" #n ")" ::: "memory")
; #define PG8_WAIT_L(n) asm volatile("s_waitcnt lgkmcnt(" #n ")" ::: "memory")
; #define PG8_BAR __builtin_amdgcn_s_barrier()
; #define PG8_SCHED __builtin_amdgcn_sched_barrier(0)
; template <class Epi, class Sched, bool ALIGN_EPI = false, bool SP2 = false>
; __device__ __forceinline__ void gemm_phase(PG8_LAS unsigned char* lds, const Gemm g, const Sched& S, const Epi& E, int wave_in) {
;     ...
;             PG8_WAIT_V(8); PG8_WAIT_L(0); PG8_BAR; PG8_MMA(0, 0, At, B0); PG8_MMA(0, 1, At, B1); PG8_BAR; PG8_SCHED;
;             PG8_LDA(At, 0, 1); PG8_STAGE(PG8_SB(0, 0), b2, voffB); PG8_STAGE(PG8_SB(0, 1), b2 + hstep, voffB); PG8_STAGE(PG8_SA(0, 0), a2, voffA);
;             PG8_WAIT_V(8); PG8_WAIT_L(0); PG8_BAR; PG8_MMA(1, 0, At, B0); PG8_MMA(1, 1, At, B1); PG8_BAR; PG8_SCHED;
;             PG8_LDB(B0, 1, 0); PG8_LDB(B1, 1, 1); PG8_SCHED; PG8_LDA(At, 1, 0); PG8_STAGE(PG8_SA(0, 1), a2 + hstep, voffA);
;             PG8_WAIT_V(8); PG8_WAIT_L(0); PG8_BAR; PG8_MMA(0, 0, At, B0); PG8_MMA(0, 1, At, B1); PG8_BAR; PG8_SCHED;
	s_setprio 1
	s_waitcnt lgkmcnt(0)
	v_mfma_f32_16x16x32_bf16 v[124:127], v[128:131], v[160:163], v[124:127]
	v_mfma_f32_16x16x32_bf16 v[60:63], v[136:139], v[160:163], v[60:63]
	v_mfma_f32_16x16x32_bf16 v[116:119], v[128:131], v[178:181], v[116:119]
	v_mfma_f32_16x16x32_bf16 v[52:55], v[136:139], v[178:181], v[52:55]
	v_mfma_f32_16x16x32_bf16 v[108:111], v[128:131], v[186:189], v[108:111]
	v_mfma_f32_16x16x32_bf16 v[44:47], v[136:139], v[186:189], v[44:47]
	v_mfma_f32_16x16x32_bf16 v[100:103], v[128:131], v[202:205], v[100:103]
	v_mfma_f32_16x16x32_bf16 v[36:39], v[136:139], v[202:205], v[36:39]
	v_mfma_f32_16x16x32_bf16 v[124:127], v[132:135], v[164:167], v[124:127]
	v_mfma_f32_16x16x32_bf16 v[60:63], v[140:143], v[164:167], v[60:63]
	v_mfma_f32_16x16x32_bf16 v[116:119], v[132:135], v[182:185], v[116:119]
	v_mfma_f32_16x16x32_bf16 v[52:55], v[140:143], v[182:185], v[52:55]
	v_mfma_f32_16x16x32_bf16 v[108:111], v[132:135], v[198:201], v[108:111]
	v_mfma_f32_16x16x32_bf16 v[44:47], v[140:143], v[198:201], v[44:47]
	v_mfma_f32_16x16x32_bf16 v[100:103], v[132:135], v[220:223], v[100:103]
	v_mfma_f32_16x16x32_bf16 v[36:39], v[140:143], v[220:223], v[36:39]
	s_setprio 0
	s_setprio 1
	v_mfma_f32_16x16x32_bf16 v[120:123], v[144:147], v[160:163], v[120:123]
	v_mfma_f32_16x16x32_bf16 v[56:59], v[152:155], v[160:163], v[56:59]
	v_mfma_f32_16x16x32_bf16 v[112:115], v[144:147], v[178:181], v[112:115]
	v_mfma_f32_16x16x32_bf16 v[48:51], v[152:155], v[178:181], v[48:51]
	v_mfma_f32_16x16x32_bf16 v[104:107], v[144:147], v[186:189], v[104:107]
	v_mfma_f32_16x16x32_bf16 v[40:43], v[152:155], v[186:189], v[40:43]
	v_mfma_f32_16x16x32_bf16 v[96:99], v[144:147], v[202:205], v[96:99]
	v_mfma_f32_16x16x32_bf16 v[32:35], v[152:155], v[202:205], v[32:35]
	v_mfma_f32_16x16x32_bf16 v[120:123], v[148:151], v[164:167], v[120:123]
	v_mfma_f32_16x16x32_bf16 v[56:59], v[156:159], v[164:167], v[56:59]
	v_mfma_f32_16x16x32_bf16 v[112:115], v[148:151], v[182:185], v[112:115]
	v_mfma_f32_16x16x32_bf16 v[48:51], v[156:159], v[182:185], v[48:51]
	v_mfma_f32_16x16x32_bf16 v[104:107], v[148:151], v[198:201], v[104:107]
	v_mfma_f32_16x16x32_bf16 v[40:43], v[156:159], v[198:201], v[40:43]
	v_mfma_f32_16x16x32_bf16 v[96:99], v[148:151], v[220:223], v[96:99]
	v_mfma_f32_16x16x32_bf16 v[32:35], v[156:159], v[220:223], v[32:35]
	s_setprio 0
	s_barrier
	s_add_i32 s76, s76, s75
	s_mov_b32 m0, s76
	ds_read_b128 v[160:163], v219 offset:16384
	ds_read_b128 v[164:167], v219 offset:17408
	ds_read_b128 v[178:181], v219 offset:18432
	ds_read_b128 v[182:185], v219 offset:19456
	ds_read_b128 v[186:189], v219 offset:20480
	ds_read_b128 v[198:201], v219 offset:21504
	ds_read_b128 v[202:205], v219 offset:22528
	ds_read_b128 v[220:223], v219 offset:23552
	global_load_lds_dwordx4 v192, s[0:1]
	s_add_i32 m0, s76, 0x2000
	s_add_u32 s76, s0, 0x40000
	s_addc_u32 s77, s1, 0
	s_add_i32 s29, s29, s75
	global_load_lds_dwordx4 v168, s[0:1]
	s_mov_b32 m0, s29
	s_nop 0
	global_load_lds_dwordx4 v192, s[76:77]
	s_add_i32 m0, s29, 0x2000
	s_nop 0
	global_load_lds_dwordx4 v168, s[76:77]
	s_mov_b32 m0, s33
	s_nop 0
	global_load_lds_dwordx4 v172, s[78:79]
	s_mov_b32 m0, s62
	s_nop 0
	global_load_lds_dwordx4 v170, s[78:79]
	s_waitcnt vmcnt(8)
	s_waitcnt lgkmcnt(0)
	s_barrier
	s_setprio 1
	s_waitcnt lgkmcnt(0)
	v_mfma_f32_16x16x32_bf16 v[92:95], v[128:131], v[160:163], v[92:95]
	v_mfma_f32_16x16x32_bf16 v[28:31], v[136:139], v[160:163], v[28:31]
	v_mfma_f32_16x16x32_bf16 v[84:87], v[128:131], v[178:181], v[84:87]
	v_mfma_f32_16x16x32_bf16 v[20:23], v[136:139], v[178:181], v[20:23]
	v_mfma_f32_16x16x32_bf16 v[76:79], v[128:131], v[186:189], v[76:79]
	v_mfma_f32_16x16x32_bf16 v[12:15], v[136:139], v[186:189], v[12:15]
	v_mfma_f32_16x16x32_bf16 v[68:71], v[128:131], v[202:205], v[68:71]
	v_mfma_f32_16x16x32_bf16 v[4:7], v[136:139], v[202:205], v[4:7]
	v_mfma_f32_16x16x32_bf16 v[92:95], v[132:135], v[164:167], v[92:95]
	v_mfma_f32_16x16x32_bf16 v[28:31], v[140:143], v[164:167], v[28:31]
	v_mfma_f32_16x16x32_bf16 v[84:87], v[132:135], v[182:185], v[84:87]
	v_mfma_f32_16x16x32_bf16 v[20:23], v[140:143], v[182:185], v[20:23]
	v_mfma_f32_16x16x32_bf16 v[76:79], v[132:135], v[198:201], v[76:79]
	v_mfma_f32_16x16x32_bf16 v[12:15], v[140:143], v[198:201], v[12:15]
	v_mfma_f32_16x16x32_bf16 v[68:71], v[132:135], v[220:223], v[68:71]
	v_mfma_f32_16x16x32_bf16 v[4:7], v[140:143], v[220:223], v[4:7]
	s_setprio 0
	s_setprio 1
	v_mfma_f32_16x16x32_bf16 v[88:91], v[144:147], v[160:163], v[88:91]
	v_mfma_f32_16x16x32_bf16 v[24:27], v[152:155], v[160:163], v[24:27]
	v_mfma_f32_16x16x32_bf16 v[80:83], v[144:147], v[178:181], v[80:83]
	v_mfma_f32_16x16x32_bf16 v[16:19], v[152:155], v[178:181], v[16:19]
	v_mfma_f32_16x16x32_bf16 v[72:75], v[144:147], v[186:189], v[72:75]
	v_mfma_f32_16x16x32_bf16 v[8:11], v[152:155], v[186:189], v[8:11]
	v_mfma_f32_16x16x32_bf16 v[64:67], v[144:147], v[202:205], v[64:67]
	v_mfma_f32_16x16x32_bf16 v[0:3], v[152:155], v[202:205], v[0:3]
	v_mfma_f32_16x16x32_bf16 v[88:91], v[148:151], v[164:167], v[88:91]
	v_mfma_f32_16x16x32_bf16 v[24:27], v[156:159], v[164:167], v[24:27]
	v_mfma_f32_16x16x32_bf16 v[80:83], v[148:151], v[182:185], v[80:83]
	v_mfma_f32_16x16x32_bf16 v[16:19], v[156:159], v[182:185], v[16:19]
	v_mfma_f32_16x16x32_bf16 v[72:75], v[148:151], v[198:201], v[72:75]
	v_mfma_f32_16x16x32_bf16 v[8:11], v[156:159], v[198:201], v[8:11]
	v_mfma_f32_16x16x32_bf16 v[64:67], v[148:151], v[220:223], v[64:67]
	v_mfma_f32_16x16x32_bf16 v[0:3], v[156:159], v[220:223], v[0:3]
	s_setprio 0
	s_barrier
; #define PG8_STAGE(bufoff, gbase, voff) do { _Pragma("unroll") for (int _i = 0; _i < 2; ++_i) \
;         __builtin_amdgcn_global_load_lds((const unsigned*)((const char*)(gbase) + (voff)[_i]), (PG8_LAS unsigned*)(lds + (bufoff) + ldsw + _i * 8192), 16, 0, 0); } while (0)
; #define PG8_LDA(dst, b, h) do { _Pragma("unroll") for (int m = 0; m < 4; ++m) _Pragma("unroll") for (int k = 0; k < 2; ++k) dst[m][k] = *(const PG8_LAS bf16x8*)(lds + PG8_SA(b, h) + aoff + m * 2048 + k * 1024); } while (0)
; #define PG8_LDB(dst, b, h) do { _Pragma("unroll") for (int n = 0; n < 2; ++n) _Pragma("unroll") for (int k = 0; k < 2; ++k) dst[n][k] = *(const PG8_LAS bf16x8*)(lds + PG8_SB(b, h) + boff + n * 2048 + k * 1024); } while (0)
; #define PG8_MMA(ai, bj, At, Bt) do { __builtin_amdgcn_s_setprio(1); _Pragma("unroll") for (int m = 0; m < 4; ++m) _Pragma("unroll") for (int n = 0; n < 2; ++n) _Pragma("unroll") for (int k = 0; k < 2; ++k) \
;         acc[ai][bj][m][n] = __builtin_amdgcn_mfma_f32_16x16x32_bf16(Bt[n][k], At[m][k], acc[ai][bj][m][n], 0, 0, 0); __builtin_amdgcn_s_setprio(0); } while (0)
; #define PG8_WAIT_V(n) asm volatile("s_waitcnt vmcnt(" #n ")" ::: "memory")
; #define PG8_WAIT_L(n) asm volatile("s_waitcnt lgkmcnt(" #n ")" ::: "memory")
; #define PG8_BAR __builtin_amdgcn_s_barrier()
; #define PG8_SCHED __builtin_amdgcn_sched_barrier(0)
; template <class Epi, class Sched, bool ALIGN_EPI = false, bool SP2 = false>
; __device__ __forceinline__ void gemm_phase(PG8_LAS unsigned char* lds, const Gemm g, const Sched& S, const Epi& E, int wave_in) {
;     ...
;             PG8_LDB(B0, 1, 0); PG8_LDB(B1, 1, 1); PG8_SCHED; PG8_LDA(At, 1, 0); PG8_STAGE(PG8_SA(0, 1), a2 + hstep, voffA);
;             PG8_WAIT_V(8); PG8_WAIT_L(0); PG8_BAR; PG8_MMA(0, 0, At, B0); PG8_MMA(0, 1, At, B1); PG8_BAR; PG8_SCHED;
;             PG8_LDA(At, 1, 1); PG8_STAGE(PG8_SB(1, 0), b3, voffB); PG8_STAGE(PG8_SB(1, 1), b3 + hstep, voffB); PG8_STAGE(PG8_SA(1, 0), a3, voffA);
;             PG8_WAIT_V(8); PG8_WAIT_L(0); PG8_BAR; PG8_MMA(1, 0, At, B0); PG8_MMA(1, 1, At, B1); PG8_BAR; PG8_SCHED;
	s_add_i32 s29, s65, 0x100
	s_add_i32 s2, s52, 0x100
	v_add_u32_e32 v140, s29, v207
	v_add_u32_e32 v156, s2, v207
	ds_read_b128 v[128:131], v140
	ds_read_b128 v[132:135], v140 offset:1024
	ds_read_b128 v[136:139], v140 offset:2048
	ds_read_b128 v[140:143], v140 offset:3072
	ds_read_b128 v[144:147], v156
	ds_read_b128 v[148:151], v156 offset:1024
	ds_read_b128 v[152:155], v156 offset:2048
	ds_read_b128 v[156:159], v156 offset:3072
	s_add_u32 s76, s78, 0x40000
	s_addc_u32 s77, s79, 0
	s_mov_b32 m0, s63
	ds_read_b128 v[160:163], v219 offset:32768
	ds_read_b128 v[164:167], v219 offset:33792
	ds_read_b128 v[178:181], v219 offset:34816
	ds_read_b128 v[182:185], v219 offset:35840
	ds_read_b128 v[186:189], v219 offset:36864
	ds_read_b128 v[198:201], v219 offset:37888
	ds_read_b128 v[202:205], v219 offset:38912
	ds_read_b128 v[220:223], v219 offset:39936
	global_load_lds_dwordx4 v172, s[76:77]
	s_mov_b32 m0, s31
	s_nop 0
	global_load_lds_dwordx4 v170, s[76:77]
	s_waitcnt vmcnt(8)
	s_waitcnt lgkmcnt(0)
	s_barrier
	s_setprio 1
	s_waitcnt lgkmcnt(0)
	v_mfma_f32_16x16x32_bf16 v[124:127], v[128:131], v[160:163], v[124:127]
	v_mfma_f32_16x16x32_bf16 v[60:63], v[136:139], v[160:163], v[60:63]
	v_mfma_f32_16x16x32_bf16 v[116:119], v[128:131], v[178:181], v[116:119]
	v_mfma_f32_16x16x32_bf16 v[52:55], v[136:139], v[178:181], v[52:55]
	v_mfma_f32_16x16x32_bf16 v[108:111], v[128:131], v[186:189], v[108:111]
	v_mfma_f32_16x16x32_bf16 v[44:47], v[136:139], v[186:189], v[44:47]
	v_mfma_f32_16x16x32_bf16 v[100:103], v[128:131], v[202:205], v[100:103]
	v_mfma_f32_16x16x32_bf16 v[36:39], v[136:139], v[202:205], v[36:39]
	v_mfma_f32_16x16x32_bf16 v[124:127], v[132:135], v[164:167], v[124:127]
	v_mfma_f32_16x16x32_bf16 v[60:63], v[140:143], v[164:167], v[60:63]
	v_mfma_f32_16x16x32_bf16 v[116:119], v[132:135], v[182:185], v[116:119]
	v_mfma_f32_16x16x32_bf16 v[52:55], v[140:143], v[182:185], v[52:55]
	v_mfma_f32_16x16x32_bf16 v[108:111], v[132:135], v[198:201], v[108:111]
	v_mfma_f32_16x16x32_bf16 v[44:47], v[140:143], v[198:201], v[44:47]
	v_mfma_f32_16x16x32_bf16 v[100:103], v[132:135], v[220:223], v[100:103]
	v_mfma_f32_16x16x32_bf16 v[36:39], v[140:143], v[220:223], v[36:39]
	s_setprio 0
	s_setprio 1
	v_mfma_f32_16x16x32_bf16 v[120:123], v[144:147], v[160:163], v[120:123]
	v_mfma_f32_16x16x32_bf16 v[56:59], v[152:155], v[160:163], v[56:59]
	v_mfma_f32_16x16x32_bf16 v[112:115], v[144:147], v[178:181], v[112:115]
	v_mfma_f32_16x16x32_bf16 v[48:51], v[152:155], v[178:181], v[48:51]
	v_mfma_f32_16x16x32_bf16 v[104:107], v[144:147], v[186:189], v[104:107]
	v_mfma_f32_16x16x32_bf16 v[40:43], v[152:155], v[186:189], v[40:43]
	v_mfma_f32_16x16x32_bf16 v[96:99], v[144:147], v[202:205], v[96:99]
	v_mfma_f32_16x16x32_bf16 v[32:35], v[152:155], v[202:205], v[32:35]
	v_mfma_f32_16x16x32_bf16 v[120:123], v[148:151], v[164:167], v[120:123]
	v_mfma_f32_16x16x32_bf16 v[56:59], v[156:159], v[164:167], v[56:59]
	v_mfma_f32_16x16x32_bf16 v[112:115], v[148:151], v[182:185], v[112:115]
	v_mfma_f32_16x16x32_bf16 v[48:51], v[156:159], v[182:185], v[48:51]
	v_mfma_f32_16x16x32_bf16 v[104:107], v[148:151], v[198:201], v[104:107]
	v_mfma_f32_16x16x32_bf16 v[40:43], v[156:159], v[198:201], v[40:43]
	v_mfma_f32_16x16x32_bf16 v[96:99], v[148:151], v[220:223], v[96:99]
	v_mfma_f32_16x16x32_bf16 v[32:35], v[156:159], v[220:223], v[32:35]
	s_setprio 0
	s_barrier
	s_add_u32 s44, s78, 0x80
	s_addc_u32 s45, s79, 0
	s_add_u32 s42, s0, 0x80
	s_addc_u32 s43, s1, 0
	s_add_i32 s29, s29, s75
	s_mov_b32 m0, s29
	ds_read_b128 v[160:163], v219 offset:49152
	ds_read_b128 v[164:167], v219 offset:50176
	ds_read_b128 v[178:181], v219 offset:51200
	ds_read_b128 v[182:185], v219 offset:52224
	ds_read_b128 v[186:189], v219 offset:53248
	ds_read_b128 v[198:201], v219 offset:54272
	ds_read_b128 v[202:205], v219 offset:55296
	ds_read_b128 v[220:223], v219 offset:56320
	global_load_lds_dwordx4 v192, s[42:43]
	s_add_i32 m0, s29, 0x2000
	s_add_u32 s0, s0, 0x40080
	s_addc_u32 s1, s1, 0
	s_add_i32 s2, s2, s75
	global_load_lds_dwordx4 v168, s[42:43]
	s_mov_b32 m0, s2
	s_nop 0
	global_load_lds_dwordx4 v192, s[0:1]
	s_add_i32 m0, s2, 0x2000
	s_nop 0
	global_load_lds_dwordx4 v168, s[0:1]
	s_mov_b32 m0, s9
	s_nop 0
	global_load_lds_dwordx4 v172, s[44:45]
	s_mov_b32 m0, s96
	s_nop 0
	global_load_lds_dwordx4 v170, s[44:45]
	s_waitcnt vmcnt(8)
	s_waitcnt lgkmcnt(0)
	s_barrier
	s_setprio 1
	s_waitcnt lgkmcnt(0)
	v_mfma_f32_16x16x32_bf16 v[92:95], v[128:131], v[160:163], v[92:95]
	v_mfma_f32_16x16x32_bf16 v[28:31], v[136:139], v[160:163], v[28:31]
	v_mfma_f32_16x16x32_bf16 v[84:87], v[128:131], v[178:181], v[84:87]
	v_mfma_f32_16x16x32_bf16 v[20:23], v[136:139], v[178:181], v[20:23]
	v_mfma_f32_16x16x32_bf16 v[76:79], v[128:131], v[186:189], v[76:79]
	v_mfma_f32_16x16x32_bf16 v[12:15], v[136:139], v[186:189], v[12:15]
	v_mfma_f32_16x16x32_bf16 v[68:71], v[128:131], v[202:205], v[68:71]
	v_mfma_f32_16x16x32_bf16 v[4:7], v[136:139], v[202:205], v[4:7]
	v_mfma_f32_16x16x32_bf16 v[92:95], v[132:135], v[164:167], v[92:95]
	v_mfma_f32_16x16x32_bf16 v[28:31], v[140:143], v[164:167], v[28:31]
	v_mfma_f32_16x16x32_bf16 v[84:87], v[132:135], v[182:185], v[84:87]
	v_mfma_f32_16x16x32_bf16 v[20:23], v[140:143], v[182:185], v[20:23]
	v_mfma_f32_16x16x32_bf16 v[76:79], v[132:135], v[198:201], v[76:79]
	v_mfma_f32_16x16x32_bf16 v[12:15], v[140:143], v[198:201], v[12:15]
	v_mfma_f32_16x16x32_bf16 v[68:71], v[132:135], v[220:223], v[68:71]
	v_mfma_f32_16x16x32_bf16 v[4:7], v[140:143], v[220:223], v[4:7]
	s_setprio 0
	s_setprio 1
	v_mfma_f32_16x16x32_bf16 v[88:91], v[144:147], v[160:163], v[88:91]
	v_mfma_f32_16x16x32_bf16 v[24:27], v[152:155], v[160:163], v[24:27]
	v_mfma_f32_16x16x32_bf16 v[80:83], v[144:147], v[178:181], v[80:83]
	v_mfma_f32_16x16x32_bf16 v[16:19], v[152:155], v[178:181], v[16:19]
	v_mfma_f32_16x16x32_bf16 v[72:75], v[144:147], v[186:189], v[72:75]
	v_mfma_f32_16x16x32_bf16 v[8:11], v[152:155], v[186:189], v[8:11]
	v_mfma_f32_16x16x32_bf16 v[64:67], v[144:147], v[202:205], v[64:67]
	v_mfma_f32_16x16x32_bf16 v[0:3], v[152:155], v[202:205], v[0:3]
	v_mfma_f32_16x16x32_bf16 v[88:91], v[148:151], v[164:167], v[88:91]
	v_mfma_f32_16x16x32_bf16 v[24:27], v[156:159], v[164:167], v[24:27]
	v_mfma_f32_16x16x32_bf16 v[80:83], v[148:151], v[182:185], v[80:83]
	v_mfma_f32_16x16x32_bf16 v[16:19], v[156:159], v[182:185], v[16:19]
	v_mfma_f32_16x16x32_bf16 v[72:75], v[148:151], v[198:201], v[72:75]
	v_mfma_f32_16x16x32_bf16 v[8:11], v[156:159], v[198:201], v[8:11]
	v_mfma_f32_16x16x32_bf16 v[64:67], v[148:151], v[220:223], v[64:67]
	v_mfma_f32_16x16x32_bf16 v[0:3], v[156:159], v[220:223], v[0:3]
	s_setprio 0
	s_barrier
	s_add_i32 s19, s19, 2
	s_add_u32 s81, s81, 0x100
	s_addc_u32 s18, s18, 0
	s_add_u32 vcc_lo, vcc_lo, 0x100
	s_addc_u32 vcc_hi, vcc_hi, 0
	s_cmp_gt_u32 s19, 13
	s_cbranch_scc0 .LBB0_897
